# gla_scan units remapped (block b -> unit (b%8)*32+b/8) so the 4 dv-slices and both directions of a segment run on one XCD and share its L2
# baseline (speedup 1.0000x reference)
.LBB0_295:
	s_and_b32 s98, s28, 7
	s_lshr_b32 s99, s28, 3
	s_lshl_b32 s98, s98, 5
	s_add_i32 s98, s98, s99
	s_bfe_u32 s2, s98, 0x10002
	s_ashr_i32 s3, s98, 3
	s_cmp_lt_i32 s3, 16
	s_cselect_b32 s26, 8, 16
	s_cmp_gt_i32 s3, 7
	s_cselect_b32 s29, s26, 0
	s_add_i32 s33, s29, s26
	s_not_b32 s26, s3
	s_sub_i32 s34, s3, s29
	s_add_i32 s35, s33, s26
	s_cmp_eq_u32 s2, 0
	s_cselect_b64 s[26:27], -1, 0
	s_and_b64 s[30:31], s[26:27], exec
	s_cselect_b32 s30, s34, s35
	s_lshl_b32 s31, s98, 6
	s_and_b32 s31, s31, 0xc0
	s_cmp_lt_i32 s30, 1
	s_cbranch_scc1 .LBB0_298
	s_lshl_b32 s94, s31, 2
	v_mov_b32_e32 v0, 0
	v_lshl_add_u64 v[16:17], v[24:25], 0, s[94:95]
	s_add_i32 s33, s33, -1
	v_mov_b32_e32 v1, v0
	v_mov_b32_e32 v2, v0
	v_mov_b32_e32 v3, v0
	v_mov_b32_e32 v4, v0
	v_mov_b32_e32 v5, v0
	v_mov_b32_e32 v6, v0
	v_mov_b32_e32 v7, v0
	v_mov_b32_e32 v8, v0
	v_mov_b32_e32 v9, v0
	v_mov_b32_e32 v10, v0
	v_mov_b32_e32 v11, v0
	v_mov_b32_e32 v12, v0
	v_mov_b32_e32 v13, v0
	v_mov_b32_e32 v14, v0
	v_mov_b32_e32 v15, v0

.LBB0_309:
	s_and_b32 s98, s18, 7
	s_lshr_b32 s99, s18, 3
	s_lshl_b32 s98, s98, 5
	s_add_i32 s98, s98, s99
	s_ashr_i32 s20, s98, 3
	s_and_b32 s19, s98, 3
	s_bfe_u32 s21, s98, 0x10002
	s_cmp_eq_u32 s21, 0
	s_cselect_b64 s[14:15], -1, 0
	s_lshl_b32 s94, s21, 9
	v_lshl_add_u64 v[38:39], v[20:21], 0, s[94:95]
	s_lshl_b32 s94, s19, 7
	v_mov_b32_e32 v96, 0
	s_mov_b32 s23, 0
	s_lshl_b32 s24, s20, 10
	s_lshl_b32 s22, s19, 6
	v_cndmask_b32_e64 v37, v25, v42, s[14:15]
	v_cndmask_b32_e64 v97, v48, v47, s[14:15]
	v_cndmask_b32_e64 v98, v50, v49, s[14:15]
	v_cndmask_b32_e64 v99, v52, v51, s[14:15]
	v_cndmask_b32_e64 v100, v54, v53, s[14:15]
	v_cndmask_b32_e64 v101, v56, v55, s[14:15]
	v_cndmask_b32_e64 v102, v58, v57, s[14:15]
	v_cndmask_b32_e64 v103, v60, v59, s[14:15]
	v_cndmask_b32_e64 v104, v62, v61, s[14:15]
	v_cndmask_b32_e64 v105, v64, v63, s[14:15]
	v_cndmask_b32_e64 v106, v66, v65, s[14:15]
	v_cndmask_b32_e64 v107, v68, v67, s[14:15]
	v_cndmask_b32_e64 v108, v70, v69, s[14:15]
	v_cndmask_b32_e64 v109, v72, v71, s[14:15]
	v_cndmask_b32_e64 v110, v74, v73, s[14:15]
	v_cndmask_b32_e64 v111, v76, v75, s[14:15]
	v_cndmask_b32_e64 v112, v77, v43, s[14:15]
	v_cndmask_b32_e64 v113, v79, v78, s[14:15]
	v_cndmask_b32_e64 v114, v81, v80, s[14:15]
	v_cndmask_b32_e64 v115, v83, v82, s[14:15]
	v_cndmask_b32_e64 v116, v85, v84, s[14:15]
	s_movk_i32 s25, 0x3c0
	v_mov_b32_e32 v0, 0
	v_mov_b32_e32 v1, v96
	v_mov_b32_e32 v2, v96
	v_mov_b32_e32 v3, v96
	v_mov_b32_e32 v4, 0
	v_mov_b32_e32 v5, v96
	v_mov_b32_e32 v6, v96
	v_mov_b32_e32 v7, v96
	v_mov_b32_e32 v8, 0
	v_mov_b32_e32 v9, v96
	v_mov_b32_e32 v10, v96
	v_mov_b32_e32 v11, v96
	v_mov_b32_e32 v12, 0
	v_mov_b32_e32 v13, v96
	v_mov_b32_e32 v14, v96
	v_mov_b32_e32 v15, v96
	v_cndmask_b32_e64 v117, v87, v86, s[14:15]
	v_cndmask_b32_e64 v118, v89, v88, s[14:15]
	v_cndmask_b32_e64 v119, v91, v90, s[14:15]
	v_lshl_add_u64 v[40:41], v[22:23], 0, s[94:95]
	s_mov_b32 s26, 0xc988000
	s_and_b64 s[2:3], s[14:15], exec
	s_cselect_b32 s2, s23, s25
	s_add_i32 s2, s2, s24
	v_add_u32_e32 v236, s2, v37
	v_ashrrev_i32_e32 v237, 31, v236
	v_lshlrev_b64 v[238:239], 10, v[236:237]
	v_lshlrev_b64 v[236:237], 9, v[236:237]
	v_lshl_add_u64 v[236:237], s[46:47], 0, v[236:237]
	v_lshl_add_u64 v[236:237], v[236:237], 0, v[176:177]
	v_add_co_u32_e64 v236, s[16:17], s26, v236
	v_lshl_add_u64 v[238:239], v[38:39], 0, v[238:239]
	s_nop 0
	v_addc_co_u32_e64 v237, s[16:17], 0, v237, s[16:17]
	global_load_dword v159, v[238:239], off sc0 sc1
	global_load_ushort v160, v[236:237], off offset:256 sc0 sc1
	v_add_u32_e32 v236, s2, v97
	v_ashrrev_i32_e32 v237, 31, v236
	v_lshlrev_b64 v[238:239], 10, v[236:237]
	v_lshlrev_b64 v[236:237], 9, v[236:237]
	v_lshl_add_u64 v[236:237], s[46:47], 0, v[236:237]
	v_lshl_add_u64 v[236:237], v[236:237], 0, v[176:177]
	v_add_co_u32_e64 v236, s[16:17], s26, v236
	v_lshl_add_u64 v[238:239], v[38:39], 0, v[238:239]
	s_nop 0
	v_addc_co_u32_e64 v237, s[16:17], 0, v237, s[16:17]
	global_load_dword v161, v[238:239], off sc0 sc1
	global_load_ushort v162, v[236:237], off offset:256 sc0 sc1
	v_add_u32_e32 v236, s2, v98
	v_ashrrev_i32_e32 v237, 31, v236
	v_lshlrev_b64 v[238:239], 10, v[236:237]
	v_lshlrev_b64 v[236:237], 9, v[236:237]
	v_lshl_add_u64 v[236:237], s[46:47], 0, v[236:237]
	v_lshl_add_u64 v[236:237], v[236:237], 0, v[176:177]
	v_add_co_u32_e64 v236, s[16:17], s26, v236
	v_lshl_add_u64 v[238:239], v[38:39], 0, v[238:239]
	s_nop 0
	v_addc_co_u32_e64 v237, s[16:17], 0, v237, s[16:17]
	global_load_dword v163, v[238:239], off sc0 sc1
	global_load_ushort v164, v[236:237], off offset:256 sc0 sc1
	v_add_u32_e32 v236, s2, v99
	v_ashrrev_i32_e32 v237, 31, v236
	v_lshlrev_b64 v[238:239], 10, v[236:237]
	v_lshlrev_b64 v[236:237], 9, v[236:237]
	v_lshl_add_u64 v[236:237], s[46:47], 0, v[236:237]
	v_lshl_add_u64 v[236:237], v[236:237], 0, v[176:177]
	v_add_co_u32_e64 v236, s[16:17], s26, v236
	v_lshl_add_u64 v[238:239], v[38:39], 0, v[238:239]
	s_nop 0
	v_addc_co_u32_e64 v237, s[16:17], 0, v237, s[16:17]
	global_load_dword v165, v[238:239], off sc0 sc1
	global_load_ushort v166, v[236:237], off offset:256 sc0 sc1
	v_add_u32_e32 v236, s2, v100
	v_ashrrev_i32_e32 v237, 31, v236
	v_lshlrev_b64 v[238:239], 10, v[236:237]
	v_lshlrev_b64 v[236:237], 9, v[236:237]
	v_lshl_add_u64 v[236:237], s[46:47], 0, v[236:237]
	v_lshl_add_u64 v[236:237], v[236:237], 0, v[176:177]
	v_add_co_u32_e64 v236, s[16:17], s26, v236
	v_lshl_add_u64 v[238:239], v[38:39], 0, v[238:239]
	s_nop 0
	v_addc_co_u32_e64 v237, s[16:17], 0, v237, s[16:17]
	global_load_dword v167, v[238:239], off sc0 sc1
	global_load_ushort v168, v[236:237], off offset:256 sc0 sc1
	v_add_u32_e32 v236, s2, v101
	v_ashrrev_i32_e32 v237, 31, v236
	v_lshlrev_b64 v[238:239], 10, v[236:237]
	v_lshlrev_b64 v[236:237], 9, v[236:237]
	v_lshl_add_u64 v[236:237], s[46:47], 0, v[236:237]
	v_lshl_add_u64 v[236:237], v[236:237], 0, v[176:177]
	v_add_co_u32_e64 v236, s[16:17], s26, v236
	v_lshl_add_u64 v[238:239], v[38:39], 0, v[238:239]
	s_nop 0
	v_addc_co_u32_e64 v237, s[16:17], 0, v237, s[16:17]
	global_load_dword v169, v[238:239], off sc0 sc1
	global_load_ushort v170, v[236:237], off offset:256 sc0 sc1
	v_add_u32_e32 v236, s2, v102
	v_ashrrev_i32_e32 v237, 31, v236
	v_lshlrev_b64 v[238:239], 10, v[236:237]
	v_lshlrev_b64 v[236:237], 9, v[236:237]
	v_lshl_add_u64 v[236:237], s[46:47], 0, v[236:237]
	v_lshl_add_u64 v[236:237], v[236:237], 0, v[176:177]
	v_add_co_u32_e64 v236, s[16:17], s26, v236
	v_lshl_add_u64 v[238:239], v[38:39], 0, v[238:239]
	s_nop 0
	v_addc_co_u32_e64 v237, s[16:17], 0, v237, s[16:17]
	global_load_dword v171, v[238:239], off sc0 sc1
	global_load_ushort v172, v[236:237], off offset:256 sc0 sc1
	v_add_u32_e32 v236, s2, v103
	v_ashrrev_i32_e32 v237, 31, v236
	v_lshlrev_b64 v[238:239], 10, v[236:237]
	v_lshlrev_b64 v[236:237], 9, v[236:237]
	v_lshl_add_u64 v[236:237], s[46:47], 0, v[236:237]
	v_lshl_add_u64 v[236:237], v[236:237], 0, v[176:177]
	v_add_co_u32_e64 v236, s[16:17], s26, v236
	v_lshl_add_u64 v[238:239], v[38:39], 0, v[238:239]
	s_nop 0
	v_addc_co_u32_e64 v237, s[16:17], 0, v237, s[16:17]
	global_load_dword v173, v[238:239], off sc0 sc1
	global_load_ushort v174, v[236:237], off offset:256 sc0 sc1
	v_add_u32_e32 v236, s2, v104
	v_ashrrev_i32_e32 v237, 31, v236
	v_lshlrev_b64 v[238:239], 10, v[236:237]
	v_lshlrev_b64 v[236:237], 9, v[236:237]
	v_lshl_add_u64 v[236:237], s[46:47], 0, v[236:237]
	v_lshl_add_u64 v[236:237], v[236:237], 0, v[176:177]
	v_add_co_u32_e64 v236, s[16:17], s26, v236
	v_lshl_add_u64 v[238:239], v[38:39], 0, v[238:239]
	s_nop 0
	v_addc_co_u32_e64 v237, s[16:17], 0, v237, s[16:17]
	global_load_dword v175, v[238:239], off sc0 sc1
	global_load_ushort v182, v[236:237], off offset:256 sc0 sc1
	v_add_u32_e32 v236, s2, v105
	v_ashrrev_i32_e32 v237, 31, v236
	v_lshlrev_b64 v[238:239], 10, v[236:237]
	v_lshlrev_b64 v[236:237], 9, v[236:237]
	v_lshl_add_u64 v[236:237], s[46:47], 0, v[236:237]
	v_lshl_add_u64 v[236:237], v[236:237], 0, v[176:177]
	v_add_co_u32_e64 v236, s[16:17], s26, v236
	v_lshl_add_u64 v[238:239], v[38:39], 0, v[238:239]
	s_nop 0
	v_addc_co_u32_e64 v237, s[16:17], 0, v237, s[16:17]
	global_load_dword v183, v[238:239], off sc0 sc1
	global_load_ushort v184, v[236:237], off offset:256 sc0 sc1
	v_add_u32_e32 v236, s2, v106
	v_ashrrev_i32_e32 v237, 31, v236
	v_lshlrev_b64 v[238:239], 10, v[236:237]
	v_lshlrev_b64 v[236:237], 9, v[236:237]
	v_lshl_add_u64 v[236:237], s[46:47], 0, v[236:237]
	v_lshl_add_u64 v[236:237], v[236:237], 0, v[176:177]
	v_add_co_u32_e64 v236, s[16:17], s26, v236
	v_lshl_add_u64 v[238:239], v[38:39], 0, v[238:239]
	s_nop 0
	v_addc_co_u32_e64 v237, s[16:17], 0, v237, s[16:17]
	global_load_dword v185, v[238:239], off sc0 sc1
	global_load_ushort v186, v[236:237], off offset:256 sc0 sc1
	v_add_u32_e32 v236, s2, v107
	v_ashrrev_i32_e32 v237, 31, v236
	v_lshlrev_b64 v[238:239], 10, v[236:237]
	v_lshlrev_b64 v[236:237], 9, v[236:237]
	v_lshl_add_u64 v[236:237], s[46:47], 0, v[236:237]
	v_lshl_add_u64 v[236:237], v[236:237], 0, v[176:177]
	v_add_co_u32_e64 v236, s[16:17], s26, v236
	v_lshl_add_u64 v[238:239], v[38:39], 0, v[238:239]
	s_nop 0
	v_addc_co_u32_e64 v237, s[16:17], 0, v237, s[16:17]
	global_load_dword v187, v[238:239], off sc0 sc1
	global_load_ushort v188, v[236:237], off offset:256 sc0 sc1
	v_add_u32_e32 v236, s2, v108
	v_ashrrev_i32_e32 v237, 31, v236
	v_lshlrev_b64 v[238:239], 10, v[236:237]
	v_lshlrev_b64 v[236:237], 9, v[236:237]
	v_lshl_add_u64 v[236:237], s[46:47], 0, v[236:237]
	v_lshl_add_u64 v[236:237], v[236:237], 0, v[176:177]
	v_add_co_u32_e64 v236, s[16:17], s26, v236
	v_lshl_add_u64 v[238:239], v[38:39], 0, v[238:239]
	s_nop 0
	v_addc_co_u32_e64 v237, s[16:17], 0, v237, s[16:17]
	global_load_dword v189, v[238:239], off sc0 sc1
	global_load_ushort v190, v[236:237], off offset:256 sc0 sc1
	v_add_u32_e32 v236, s2, v109
	v_ashrrev_i32_e32 v237, 31, v236
	v_lshlrev_b64 v[238:239], 10, v[236:237]
	v_lshlrev_b64 v[236:237], 9, v[236:237]
	v_lshl_add_u64 v[236:237], s[46:47], 0, v[236:237]
	v_lshl_add_u64 v[236:237], v[236:237], 0, v[176:177]
	v_add_co_u32_e64 v236, s[16:17], s26, v236
	v_lshl_add_u64 v[238:239], v[38:39], 0, v[238:239]
	s_nop 0
	v_addc_co_u32_e64 v237, s[16:17], 0, v237, s[16:17]
	global_load_dword v191, v[238:239], off sc0 sc1
	global_load_ushort v192, v[236:237], off offset:256 sc0 sc1
	v_add_u32_e32 v236, s2, v110
	v_ashrrev_i32_e32 v237, 31, v236
	v_lshlrev_b64 v[238:239], 10, v[236:237]
	v_lshlrev_b64 v[236:237], 9, v[236:237]
	v_lshl_add_u64 v[236:237], s[46:47], 0, v[236:237]
	v_lshl_add_u64 v[236:237], v[236:237], 0, v[176:177]
	v_add_co_u32_e64 v236, s[16:17], s26, v236
	v_lshl_add_u64 v[238:239], v[38:39], 0, v[238:239]
	s_nop 0
	v_addc_co_u32_e64 v237, s[16:17], 0, v237, s[16:17]
	global_load_dword v193, v[238:239], off sc0 sc1
	global_load_ushort v194, v[236:237], off offset:256 sc0 sc1
	v_add_u32_e32 v236, s2, v111
	v_ashrrev_i32_e32 v237, 31, v236
	v_lshlrev_b64 v[238:239], 10, v[236:237]
	v_lshlrev_b64 v[236:237], 9, v[236:237]
	v_lshl_add_u64 v[236:237], s[46:47], 0, v[236:237]
	v_lshl_add_u64 v[236:237], v[236:237], 0, v[176:177]
	v_add_co_u32_e64 v236, s[16:17], s26, v236
	v_lshl_add_u64 v[238:239], v[38:39], 0, v[238:239]
	s_nop 0
	v_addc_co_u32_e64 v237, s[16:17], 0, v237, s[16:17]
	global_load_dword v195, v[238:239], off sc0 sc1
	global_load_ushort v196, v[236:237], off offset:256 sc0 sc1
	v_add_u32_e32 v236, s2, v112
	v_ashrrev_i32_e32 v237, 31, v236
	v_lshlrev_b64 v[236:237], 9, v[236:237]
	v_lshl_add_u64 v[236:237], v[40:41], 0, v[236:237]
	global_load_ushort v197, v[236:237], off sc0 sc1
	v_add_u32_e32 v236, s2, v113
	v_ashrrev_i32_e32 v237, 31, v236
	v_lshlrev_b64 v[236:237], 9, v[236:237]
	v_lshl_add_u64 v[236:237], v[40:41], 0, v[236:237]
	global_load_ushort v198, v[236:237], off sc0 sc1
	v_add_u32_e32 v236, s2, v114
	v_ashrrev_i32_e32 v237, 31, v236
	v_lshlrev_b64 v[236:237], 9, v[236:237]
	v_lshl_add_u64 v[236:237], v[40:41], 0, v[236:237]
	global_load_ushort v199, v[236:237], off sc0 sc1
	v_add_u32_e32 v236, s2, v115
	v_ashrrev_i32_e32 v237, 31, v236
	v_lshlrev_b64 v[236:237], 9, v[236:237]
	v_lshl_add_u64 v[236:237], v[40:41], 0, v[236:237]
	global_load_ushort v200, v[236:237], off sc0 sc1
	v_add_u32_e32 v236, s2, v116
	v_ashrrev_i32_e32 v237, 31, v236
	v_lshlrev_b64 v[236:237], 9, v[236:237]
	v_lshl_add_u64 v[236:237], v[40:41], 0, v[236:237]
	global_load_ushort v201, v[236:237], off sc0 sc1
	v_add_u32_e32 v236, s2, v117
	v_ashrrev_i32_e32 v237, 31, v236
	v_lshlrev_b64 v[236:237], 9, v[236:237]
	v_lshl_add_u64 v[236:237], v[40:41], 0, v[236:237]
	global_load_ushort v213, v[236:237], off sc0 sc1
	v_add_u32_e32 v236, s2, v118
	v_ashrrev_i32_e32 v237, 31, v236
	v_lshlrev_b64 v[236:237], 9, v[236:237]
	v_lshl_add_u64 v[236:237], v[40:41], 0, v[236:237]
	global_load_ushort v214, v[236:237], off sc0 sc1
	v_add_u32_e32 v236, s2, v119
	v_ashrrev_i32_e32 v237, 31, v236
	v_lshlrev_b64 v[236:237], 9, v[236:237]
	v_lshl_add_u64 v[236:237], v[40:41], 0, v[236:237]
	global_load_ushort v215, v[236:237], off sc0 sc1
	s_branch .LBB0_311
